# re-measure of the K-fragment offset:256 address-reuse version (current best)
# baseline (speedup 1.0000x reference)
; #define RT_BAR() do { asm volatile("s_waitcnt lgkmcnt(0)" ::: "memory"); __builtin_amdgcn_s_barrier(); asm volatile("" ::: "memory"); } while (0)
; __device__ __forceinline__ void p2_ret(const Frame& F, ArgsP a, int layer) {
;     ...
;     for (int it = F.vcu; it < BATCH * RH * 8; it += F.G) {
;         const int bh = it >> 3, p = it & 7, b = bh >> 3, h = bh & 7;
;         const float e = __builtin_amdgcn_exp2f((float)(-5 - h));
;         const float lg2 = -(e * (1.f + e * (0.5f + e * (0.33333334f + e * (0.25f + e * (0.2f + e * 0.16666667f)))))) * 1.4426950408889634f;
;     ...
;         bf16x8 qf[16];
;         RT_PREFETCH(15 - p);
;         for (int uu = 0; uu < 2; ++uu) {
;             const int qi = uu ? p : 15 - p, ntile = 2 * (qi + 1);
;             const size_t tokq = (size_t)b * SEQ + qi * 128;
;             f32x16 oacc[4];
; #pragma unroll
;             for (int db = 0; db < 4; ++db)
; #pragma unroll
;                 for (int r = 0; r < 16; ++r) oacc[db][r] = 0.f;
;             asm volatile("s_waitcnt vmcnt(0)" ::: "memory"); RT_BAR();
.LBB0_352:
	s_waitcnt vmcnt(0)
	s_waitcnt lgkmcnt(0)
	s_barrier
	v_readlane_b32 s2, v255, 15
	s_add_i32 s95, s95, s2
	v_readlane_b32 s36, v255, 38
	s_cmpk_gt_i32 s95, 0x1ff
	s_cbranch_scc1 .LBB0_465
.LBB0_353:
	s_and_b32 s50, s95, 7
	s_ashr_i32 s2, s95, 6
	s_and_b32 s2, s2, 3
	s_ashr_i32 s3, s2, 31
	s_xor_b32 s89, s50, 15
	s_lshl_b64 s[66:67], s[2:3], 11
	v_lshl_or_b32 v0, s89, 7, v226
	v_or_b32_e32 v34, s66, v0
	v_mov_b32_e32 v35, s67
	v_readlane_b32 s6, v255, 30
	s_bfe_u32 s4, s95, 0x30003
	v_lshlrev_b64 v[36:37], 12, v[34:35]
	v_readlane_b32 s7, v255, 31
	s_lshl_b32 s20, s4, 9
	v_mov_b32_e32 v221, v1
	v_lshl_add_u64 v[36:37], s[6:7], 0, v[36:37]
	v_lshl_add_u64 v[36:37], v[36:37], 0, s[20:21]
	v_lshl_add_u64 v[36:37], v[36:37], 0, v[220:221]
	global_load_dwordx4 v[118:121], v[36:37], off
	global_load_dwordx4 v[122:125], v[36:37], off offset:32
	global_load_dwordx4 v[126:129], v[36:37], off offset:64
	global_load_dwordx4 v[130:133], v[36:37], off offset:96
	global_load_dwordx4 v[134:137], v[36:37], off offset:128
	global_load_dwordx4 v[138:141], v[36:37], off offset:160
	global_load_dwordx4 v[142:145], v[36:37], off offset:192
	global_load_dwordx4 v[146:149], v[36:37], off offset:224
	global_load_dwordx4 v[150:153], v[36:37], off offset:256
	global_load_dwordx4 v[154:157], v[36:37], off offset:288
	global_load_dwordx4 v[158:161], v[36:37], off offset:320
	global_load_dwordx4 v[162:165], v[36:37], off offset:352
	global_load_dwordx4 v[166:169], v[36:37], off offset:384
	global_load_dwordx4 v[170:173], v[36:37], off offset:416
	global_load_dwordx4 v[174:177], v[36:37], off offset:448
	global_load_dwordx4 v[178:181], v[36:37], off offset:480
	s_lshl_b32 s5, s2, 23
	s_mov_b32 m0, s22
	s_or_b32 s17, s20, s5
	v_readlane_b32 s5, v254, 8
	buffer_load_dwordx4 v224, s[40:43], s17 offen lds
	s_or_b32 s56, s17, 0x10000
	s_mov_b32 m0, s5
	v_readlane_b32 s5, v254, 9
	buffer_load_dwordx4 v224, s[40:43], s56 offen lds
	s_or_b32 s57, s17, 0x20000
	s_mov_b32 m0, s5
	v_readlane_b32 s5, v254, 10
	s_lshl_b32 s3, s2, 11
	buffer_load_dwordx4 v224, s[40:43], s57 offen lds
	s_mov_b32 m0, s5
	s_lshl_b32 s5, s4, 21
	s_or_b32 s34, s17, 0x30000
	s_add_i32 s5, s5, s3
	buffer_load_dwordx4 v224, s[40:43], s34 offen lds
	s_lshl_b32 s10, s5, 1
	s_mov_b32 s46, s42
	s_mov_b32 s47, s43
	s_mov_b32 m0, s33
	v_readlane_b32 s3, v254, 12
	buffer_load_dwordx4 v225, s[44:47], s10 offen lds
	s_add_i32 s52, s10, 0x100000
	s_mov_b32 m0, s3
	v_readlane_b32 s3, v254, 13
	buffer_load_dwordx4 v225, s[44:47], s52 offen lds
	s_add_i32 s65, s10, 0x200000
	s_mov_b32 m0, s3
	v_readlane_b32 s3, v254, 14
	buffer_load_dwordx4 v225, s[44:47], s65 offen lds
	s_add_i32 s16, s10, 0x300000
	s_mov_b32 m0, s3
	s_sub_i32 s3, -5, s4
	buffer_load_dwordx4 v225, s[44:47], s16 offen lds
	s_add_i32 m0, s22, 0x8000
	s_add_i32 s12, s17, 0x40000
	buffer_load_dwordx4 v224, s[40:43], s12 offen lds
	s_add_i32 m0, s22, 0xa000
	s_add_i32 s12, s17, 0x50000
	buffer_load_dwordx4 v224, s[40:43], s12 offen lds
	s_add_i32 m0, s22, 0xc000
	s_add_i32 s12, s17, 0x60000
	buffer_load_dwordx4 v224, s[40:43], s12 offen lds
	s_add_i32 m0, s22, 0xe000
	s_add_i32 s12, s17, 0x70000
	buffer_load_dwordx4 v224, s[40:43], s12 offen lds
	v_cvt_f32_i32_e32 v0, s3
	s_lshl_b32 s25, s4, 22
	s_lshl_b32 s3, s4, 8
	v_readlane_b32 s4, v255, 32
	v_exp_f32_e32 v0, v0
	s_add_u32 s68, s4, s20
	v_readlane_b32 s4, v255, 34
	v_lshl_add_u64 v[36:37], v[210:211], 0, s[20:21]
	v_fmamk_f32 v34, v0, 0x3e2aaaab, v233
	v_fmaak_f32 v34, v0, v34, 0x3e800000
	v_fmaak_f32 v34, v0, v34, 0x3eaaaaab
	v_fma_f32 v34, v0, v34, 0.5
	v_fma_f32 v34, v0, v34, 1.0
	v_mul_f32_e32 v0, v0, v34
	v_mul_f32_e32 v221, 0xbfb8aa3b, v0
	v_lshl_or_b32 v0, s50, 7, v226
	v_or_b32_e32 v34, s66, v0
	v_lshlrev_b64 v[34:35], 12, v[34:35]
	s_addc_u32 s69, s4, 0
	s_lshl_b32 s2, s2, 12
	v_lshl_add_u64 v[222:223], v[36:37], 0, v[34:35]
	s_add_i32 s25, s25, s2
	s_or_b32 s88, s17, 0x70000
	s_mov_b64 s[74:75], -1
	s_lshl_b32 s20, s3, 1
	s_branch .LBB0_355

; __device__ __forceinline__ CvU cv_decode(ArgsP a, unsigned char* ws, int hi, int layer) {
;     CvU u; int fi = hi >> 1; const int half = hi & 1; int l = layer, kind;
;     if (fi < CV_GLU) kind = 0; else if ((fi -= CV_GLU) < CV_OUT) kind = 1; else { fi -= CV_OUT; kind = 2; l = layer + 1; }
;     int kb, nb;
;     if (kind == 0) { u.W = a->in[I_WGLU] + (size_t)l * DS * DS; u.WT = (bf16_t*)(ws + WS_WTGLU + (size_t)l * DS * DS); u.K = DS; u.N = DS; kb = fi / (DS / 64); nb = fi % (DS / 64); }
;     else if (kind == 1) { u.W = a->in[I_WOUT] + (size_t)l * DM * DM; u.WT = (bf16_t*)(ws + WS_WTOUT) + (size_t)l * DM * DM; u.K = DM; u.N = DM; kb = fi / (DM / 64); nb = fi % (DM / 64); }
;     else { u.W = a->in[I_WIN] + (size_t)l * DM * NPROJ; u.WT = (bf16_t*)(ws + WS_WTIN) + (size_t)l * NPROJ * DM; u.K = DM; u.N = NPROJ; kb = fi / (NPROJ / 64); nb = fi % (NPROJ / 64); }
;     u.k0 = 64 * kb + 32 * half; u.n0 = 64 * nb; u.n0d = u.n0; u.rowperm = 0;
;     u.ks = nullptr; u.f8 = (kind == 0);
;     if (kind == 1) u.ks = (u.k0 < DS) ? a->in[I_SNW] + l * DS + u.k0 : a->in[I_RNW] + l * DR + (u.k0 - DS);
;     if (kind == 2) { u.ks = a->in[I_NORMW] + l * DM + u.k0;
;         int n0 = u.n0; if (n0 >= 10240) n0 -= 2048; else if (n0 >= 8192) n0 += 2048;
;         if (n0 >= 4096 && n0 < 8192) { const int m = (n0 >> 6) & 3; n0 = (n0 & ~255) + 128 * (m & 1) + 32 * (m >> 1); u.rowperm = 1; }
;         u.n0d = n0; }
;     return u;
; }
.LBB0_366:
	s_xor_b64 s[46:47], s[70:71], -1
	s_ashr_i32 s13, s12, 31
	s_mov_b64 s[6:7], -1
	s_and_b64 vcc, exec, s[46:47]
	s_cbranch_vccz .LBB0_368
	s_cmpk_gt_i32 s95, 0xff
	s_cbranch_scc1 .LBB0_368
	s_load_dwordx2 s[6:7], s[0:1], 0x10
	s_mul_i32 s46, s12, 0xc000000
	s_mul_hi_i32 s14, s12, 0xc000000
	s_mul_hi_i32 s76, s15, 0x2aaaaaab
	s_waitcnt lgkmcnt(0)
	s_add_u32 s46, s6, s46
	s_addc_u32 s47, s7, s14
	s_lshr_b32 s6, s76, 31
	s_ashr_i32 s7, s76, 5
	s_add_i32 s84, s7, s6
	s_mul_i32 s6, s84, 0xc0
	s_sub_i32 s14, s15, s6
	s_mov_b64 s[6:7], 0
.LBB0_368:
	s_andn2_b64 vcc, exec, s[6:7]
	s_mov_b64 s[76:77], 0x3000
	s_cbranch_vccnz .LBB0_370
	s_cmpk_gt_i32 s95, 0xff
	s_cbranch_scc1 .LBB0_370
	s_load_dwordx2 s[6:7], s[0:1], 0x78
	s_lshl_b64 s[46:47], s[12:13], 26
	s_mov_b64 s[76:77], 0x1000
	s_waitcnt lgkmcnt(0)
	s_add_u32 s46, s6, s46
	s_addc_u32 s47, s7, s47
	s_ashr_i32 s6, s15, 31
	s_lshr_b32 s6, s6, 26
	s_add_i32 s6, s15, s6
	s_ashr_i32 s84, s6, 6
	s_andn2_b32 s6, s6, 63
	s_sub_i32 s14, s15, s6

; __device__ __forceinline__ CvU cv_decode(ArgsP a, unsigned char* ws, int hi, int layer) {
;     ...
;     if (kind == 0) { u.W = a->in[I_WGLU] + (size_t)l * DS * DS; u.WT = (bf16_t*)(ws + WS_WTGLU + (size_t)l * DS * DS); u.K = DS; u.N = DS; kb = fi / (DS / 64); nb = fi % (DS / 64); }
;     else if (kind == 1) { u.W = a->in[I_WOUT] + (size_t)l * DM * DM; u.WT = (bf16_t*)(ws + WS_WTOUT) + (size_t)l * DM * DM; u.K = DM; u.N = DM; kb = fi / (DM / 64); nb = fi % (DM / 64); }
;     else { u.W = a->in[I_WIN] + (size_t)l * DM * NPROJ; u.WT = (bf16_t*)(ws + WS_WTIN) + (size_t)l * NPROJ * DM; u.K = DM; u.N = NPROJ; kb = fi / (NPROJ / 64); nb = fi % (NPROJ / 64); }
;     u.k0 = 64 * kb + 32 * half; u.n0 = 64 * nb; u.n0d = u.n0; u.rowperm = 0;
;     u.ks = nullptr; u.f8 = (kind == 0);
;     if (kind == 1) u.ks = (u.k0 < DS) ? a->in[I_SNW] + l * DS + u.k0 : a->in[I_RNW] + l * DR + (u.k0 - DS);
;     if (kind == 2) { u.ks = a->in[I_NORMW] + l * DM + u.k0;
;         int n0 = u.n0; if (n0 >= 10240) n0 -= 2048; else if (n0 >= 8192) n0 += 2048;
;         if (n0 >= 4096 && n0 < 8192) { const int m = (n0 >> 6) & 3; n0 = (n0 & ~255) + 128 * (m & 1) + 32 * (m >> 1); u.rowperm = 1; }
;         u.n0d = n0; }
;     return u;
; }
; __device__ __forceinline__ void cv_load(const CvU& u, int lane, f32x4 (&v)[8], f32x4 (&sc)[2]) {
;     const int nq = lane & 15, kq = lane >> 4;
;     const float* wp = u.W + (size_t)(u.k0 + 8 * kq) * u.N + u.n0 + 4 * nq;
; #pragma unroll
;     for (int i = 0; i < 8; ++i) v[i] = __builtin_nontemporal_load((const f32x4*)(wp + (size_t)i * u.N));
;     if (u.ks) { sc[0] = *(const f32x4*)(u.ks + 8 * kq); sc[1] = *(const f32x4*)(u.ks + 8 * kq + 4); }
;     else { sc[0] = (f32x4){1.f, 1.f, 1.f, 1.f}; sc[1] = sc[0]; }
; }
.LBB0_371:
	s_andn2_b64 vcc, exec, s[78:79]
	s_cbranch_vccnz .LBB0_373
	s_cmpk_gt_i32 s95, 0xff
	s_cbranch_scc1 .LBB0_373
	s_load_dwordx2 s[6:7], s[0:1], 0x58
	s_ashr_i32 s13, s12, 31
	s_lshl_b64 s[46:47], s[12:13], 24
	s_mov_b64 s[76:77], 0x800
	s_waitcnt lgkmcnt(0)
	s_add_u32 s46, s6, s46
	s_addc_u32 s47, s7, s47
	s_ashr_i32 s6, s15, 31
	s_lshr_b32 s6, s6, 27
	s_add_i32 s6, s15, s6
	s_ashr_i32 s84, s6, 5
	s_andn2_b32 s6, s6, 31
	s_sub_i32 s14, s15, s6
.LBB0_373:
	s_lshl_b32 s7, s36, 5
	s_lshl_b32 s6, s84, 6
	s_and_b32 s7, s7, 32
	s_or_b32 s6, s6, s7
	s_andn2_b64 vcc, exec, s[70:71]
	s_mov_b64 s[70:71], 0
	s_cbranch_vccnz .LBB0_378
	s_lshl_b32 s78, s12, 11
	s_ashr_i32 s79, s78, 31
	s_cmpk_gt_i32 s6, 0x7ff
	s_mov_b64 s[84:85], -1
	s_cbranch_scc0 .LBB0_376
	s_cmpk_gt_i32 s95, 0xff
	s_cbranch_scc1 .LBB0_376
	s_load_dwordx2 s[70:71], s[0:1], 0x70
	s_lshl_b64 s[84:85], s[78:79], 2
	s_mov_b32 s7, s21
	s_waitcnt lgkmcnt(0)
	s_add_u32 s13, s70, s84
	s_addc_u32 s15, s71, s85
	s_lshl_b64 s[70:71], s[6:7], 2
	s_add_u32 s7, s13, s70
	s_addc_u32 s13, s15, s71
	s_add_u32 s70, s7, 0xffffe000
	s_addc_u32 s71, s13, -1
	s_mov_b64 s[84:85], 0
.LBB0_376:
	s_andn2_b64 vcc, exec, s[84:85]
	s_cbranch_vccnz .LBB0_378
	s_cmpk_gt_i32 s95, 0xff
	s_cbranch_scc1 .LBB0_378
	s_load_dwordx2 s[70:71], s[0:1], 0x68
	s_lshl_b64 s[78:79], s[78:79], 2
	s_waitcnt lgkmcnt(0)
	s_add_u32 s13, s70, s78
	s_addc_u32 s15, s71, s79
	s_ashr_i32 s7, s6, 31
	s_lshl_b64 s[70:71], s[6:7], 2
	s_add_u32 s70, s13, s70
	s_addc_u32 s71, s15, s71
.LBB0_378:
	s_andn2_b64 vcc, exec, s[4:5]
	s_mov_b64 s[78:79], s[62:63]
	s_cbranch_vccnz .LBB0_380
	s_cmpk_gt_i32 s95, 0xff
	s_cbranch_scc1 .LBB0_380
	s_load_dwordx2 s[4:5], s[0:1], 0x8
	s_lshl_b32 s12, s12, 12
	s_ashr_i32 s13, s12, 31
	s_ashr_i32 s7, s6, 31
	s_lshl_b64 s[12:13], s[12:13], 2
	s_waitcnt lgkmcnt(0)
	s_add_u32 s12, s4, s12
	s_addc_u32 s13, s5, s13
	s_lshl_b64 s[4:5], s[6:7], 2
	s_add_u32 s70, s12, s4
	s_addc_u32 s71, s13, s5
.LBB0_380:
	s_cmpk_gt_i32 s95, 0xff
	s_cbranch_scc1 .LBB0_383
	v_or_b32_e32 v0, s6, v206
	s_ashr_i32 s5, s6, 31
	s_waitcnt vmcnt(15)
	v_mul_lo_u32 v4, s77, v0
	s_mul_i32 s5, s76, s5
	v_mad_u64_u32 v[2:3], s[6:7], s76, v0, 0
	s_lshl_b32 s4, s14, 6
	v_add3_u32 v3, v3, s5, v4
	v_lshl_add_u64 v[2:3], v[2:3], 2, s[46:47]
	s_ashr_i32 s5, s4, 31
	v_lshl_add_u64 v[2:3], s[4:5], 2, v[2:3]
	v_lshlrev_b32_e32 v0, 2, v208
	v_lshl_add_u64 v[2:3], v[2:3], 0, v[0:1]
	s_lshl_b64 s[4:5], s[76:77], 2
	s_waitcnt vmcnt(13)
	v_lshl_add_u64 v[10:11], v[2:3], 0, s[4:5]
	global_load_dwordx4 v[2:5], v[2:3], off nt
	s_nop 0
	global_load_dwordx4 v[6:9], v[10:11], off nt
	v_lshl_add_u64 v[10:11], v[10:11], 0, s[4:5]
	s_waitcnt vmcnt(13)
	v_lshl_add_u64 v[18:19], v[10:11], 0, s[4:5]
	global_load_dwordx4 v[10:13], v[10:11], off nt
	s_nop 0
	global_load_dwordx4 v[14:17], v[18:19], off nt
	v_lshl_add_u64 v[18:19], v[18:19], 0, s[4:5]
	s_waitcnt vmcnt(13)
	v_lshl_add_u64 v[26:27], v[18:19], 0, s[4:5]
	global_load_dwordx4 v[18:21], v[18:19], off nt
	s_nop 0
	global_load_dwordx4 v[22:25], v[26:27], off nt
	v_lshl_add_u64 v[26:27], v[26:27], 0, s[4:5]
	s_waitcnt vmcnt(14)
	v_lshl_add_u64 v[30:31], v[26:27], 0, s[4:5]
	global_load_dwordx4 v[26:29], v[26:27], off nt
	s_nop 0
	global_load_dwordx4 v[30:33], v[30:31], off nt
	s_cmp_eq_u64 s[70:71], 0
	s_cbranch_scc1 .LBB0_382
	v_lshlrev_b32_e32 v0, 2, v206
	global_load_dwordx4 v[182:185], v0, s[70:71] offset:16
	global_load_dwordx4 v[186:189], v0, s[70:71]
	s_branch .LBB0_383

; __device__ __forceinline__ CvU cv_decode(ArgsP a, unsigned char* ws, int hi, int layer) {
;     CvU u; int fi = hi >> 1; const int half = hi & 1; int l = layer, kind;
;     if (fi < CV_GLU) kind = 0; else if ((fi -= CV_GLU) < CV_OUT) kind = 1; else { fi -= CV_OUT; kind = 2; l = layer + 1; }
;     int kb, nb;
;     if (kind == 0) { u.W = a->in[I_WGLU] + (size_t)l * DS * DS; u.WT = (bf16_t*)(ws + WS_WTGLU + (size_t)l * DS * DS); u.K = DS; u.N = DS; kb = fi / (DS / 64); nb = fi % (DS / 64); }
;     else if (kind == 1) { u.W = a->in[I_WOUT] + (size_t)l * DM * DM; u.WT = (bf16_t*)(ws + WS_WTOUT) + (size_t)l * DM * DM; u.K = DM; u.N = DM; kb = fi / (DM / 64); nb = fi % (DM / 64); }
;     else { u.W = a->in[I_WIN] + (size_t)l * DM * NPROJ; u.WT = (bf16_t*)(ws + WS_WTIN) + (size_t)l * NPROJ * DM; u.K = DM; u.N = NPROJ; kb = fi / (NPROJ / 64); nb = fi % (NPROJ / 64); }
;     u.k0 = 64 * kb + 32 * half; u.n0 = 64 * nb; u.n0d = u.n0; u.rowperm = 0;
.Lrk_wd:
	s_and_b64 vcc, exec, s[38:39]
	s_cbranch_vccnz .LBB0_357
	s_cmpk_gt_i32 s95, 0xff
	s_cbranch_scc1 .LBB0_356
	s_ashr_i32 s14, s36, 1
	s_cmpk_lt_i32 s14, 0x400
	s_cselect_b64 s[4:5], -1, 0
	s_mov_b64 s[70:71], 0
	s_and_b64 vcc, exec, s[4:5]
	s_cbranch_vccnz .LBB0_394
	s_mov_b64 s[46:47], -1
	s_cmpk_gt_u32 s14, 0x13ff
	s_mov_b64 s[6:7], -1
	s_cbranch_scc0 .LBB0_391
	s_add_i32 s12, s14, 0xffffec00
	s_mov_b64 s[6:7], 0
